# phase 0 input conversion loop: four row loads issued together instead of load-wait-store one at a time
# speedup vs baseline: 1.0024x; 1.0024x over previous
; DI unsigned pk2(float lo, float hi) { f32x2 v = {lo, hi}; bfv2 b = __builtin_convertvector(v, bfv2); return __builtin_bit_cast(unsigned, b); }
; DI size_t tidxA(int row, int k) { return ((size_t)(row >> 8) * 32 + (k >> 5)) * 8192 + (size_t)(swz_chunk(row & 255, (k & 31) >> 3) * 8 + (k & 7)); }
; DI void phase0(const Params& p, unsigned char* lds) {
;     ...
;   for (int row = bid * 4 + wid; row < T_TOK; row += nb * 4) {
;     const float* src = row < T_PROMPT ? p.x_prompt + (size_t)row * 1024 : p.x_sample + (size_t)(row - T_PROMPT) * 1024;
;     float s = 0.f;
; #pragma unroll
;     for (int i = 0; i < 4; ++i) {
;       const f32x4 v = *(const f32x4*)(src + i * 256 + lane * 4);
;       s += v.x * v.x + v.y * v.y + v.z * v.z + v.w * v.w;
;       *(u32x2*)(xb + tidxA(row, i * 256 + lane * 4)) = (u32x2){pk2(v.x, v.y), pk2(v.z, v.w)};
;     }
; #pragma unroll
;     for (int o = 32; o >= 1; o >>= 1) s += __shfl_xor(s, o);
;     if (lane == 0) ssq[row] = s;
;   }
.LBB0_414:
	v_add_u32_e32 v5, 0xffff8000, v2
	v_cmp_gt_i32_e64 s[0:1], s28, v2
	s_waitcnt lgkmcnt(0)
	v_mov_b32_e32 v15, s49
	v_ashrrev_i32_e32 v20, 8, v2
	v_cndmask_b32_e64 v16, v5, v2, s[0:1]
	v_mov_b32_e32 v5, s51
	v_cndmask_b32_e64 v17, 0, v3, s[0:1]
	v_cndmask_b32_e64 v19, v5, v15, s[0:1]
	v_mov_b32_e32 v5, s50
	v_mov_b32_e32 v15, s48
	v_cndmask_b32_e64 v18, v5, v15, s[0:1]
	v_lshlrev_b64 v[16:17], 12, v[16:17]
	v_lshl_add_u64 v[16:17], v[18:19], 0, v[16:17]
	v_lshl_add_u64 v[28:29], v[16:17], 0, v[160:161]
	global_load_dwordx4 v[16:19], v[28:29], off
	global_load_dwordx4 v[36:39], v[28:29], off offset:1024
	global_load_dwordx4 v[40:43], v[28:29], off offset:2048
	global_load_dwordx4 v[44:47], v[28:29], off offset:3072
	v_lshrrev_b32_e32 v22, 2, v2
	v_and_b32_e32 v15, 0x3fc, v13
	v_ashrrev_i32_e32 v21, 31, v20
	v_xor_b32_e32 v22, v22, v6
	v_and_or_b32 v15, v22, 3, v15
	v_lshlrev_b64 v[20:21], 19, v[20:21]
	v_mov_b32_e32 v23, v161
	v_lshl_add_u64 v[20:21], s[10:11], 0, v[20:21]
	v_lshl_or_b32 v22, v15, 4, v14
	v_mov_b32_e32 v5, v161
	v_lshl_add_u64 v[20:21], v[20:21], 0, v[22:23]
	v_lshl_add_u64 v[32:33], v[20:21], 0, v[4:5]
	s_mov_b32 s0, 0x20000
	v_add_co_u32_e64 v24, s[0:1], s0, v32
	s_waitcnt vmcnt(3)
	v_cvt_pk_bf16_f32 v20, v16, v17
	v_cvt_pk_bf16_f32 v21, v18, v19
	global_store_dwordx2 v[32:33], v[20:21], off
	v_addc_co_u32_e64 v25, s[0:1], 0, v33, s[0:1]
	s_mov_b32 s0, 0x40000
	s_nop 0
	v_add_co_u32_e64 v30, s[0:1], s0, v32
	v_mul_f32_e32 v5, v17, v17
	s_nop 0
	v_addc_co_u32_e64 v31, s[0:1], 0, v33, s[0:1]
	v_fmac_f32_e32 v5, v16, v16
	v_fmac_f32_e32 v5, v18, v18
	v_fmac_f32_e32 v5, v19, v19
	s_mov_b32 s0, 0x60000
	v_add_co_u32_e64 v18, s[0:1], s0, v32
	s_waitcnt vmcnt(3)
	v_cvt_pk_bf16_f32 v26, v36, v37
	v_cvt_pk_bf16_f32 v27, v38, v39
	global_store_dwordx2 v[24:25], v[26:27], off
	v_mul_f32_e32 v15, v37, v37
	v_fmac_f32_e32 v15, v36, v36
	v_fmac_f32_e32 v15, v38, v38
	v_fmac_f32_e32 v15, v39, v39
	v_add_f32_e32 v5, v5, v15
	v_addc_co_u32_e64 v19, s[0:1], 0, v33, s[0:1]
	s_waitcnt vmcnt(3)
	v_cvt_pk_bf16_f32 v34, v40, v41
	v_cvt_pk_bf16_f32 v35, v42, v43
	global_store_dwordx2 v[30:31], v[34:35], off
	v_mul_f32_e32 v15, v41, v41
	v_fmac_f32_e32 v15, v40, v40
	v_fmac_f32_e32 v15, v42, v42
	v_fmac_f32_e32 v15, v43, v43
	v_add_f32_e32 v5, v5, v15
	s_waitcnt vmcnt(3)
	v_mul_f32_e32 v15, v45, v45
	v_fmac_f32_e32 v15, v44, v44
	v_fmac_f32_e32 v15, v46, v46
	v_fmac_f32_e32 v15, v47, v47
	v_add_f32_e32 v5, v5, v15
	ds_bpermute_b32 v15, v7, v5
	v_cvt_pk_bf16_f32 v16, v44, v45
	v_cvt_pk_bf16_f32 v17, v46, v47
	global_store_dwordx2 v[18:19], v[16:17], off
	s_waitcnt lgkmcnt(0)
	v_add_f32_e32 v5, v5, v15
	ds_bpermute_b32 v15, v8, v5
	s_waitcnt lgkmcnt(0)
	v_add_f32_e32 v5, v5, v15
	ds_bpermute_b32 v15, v9, v5
	s_waitcnt lgkmcnt(0)
	v_add_f32_e32 v5, v5, v15
	ds_bpermute_b32 v15, v10, v5
	s_waitcnt lgkmcnt(0)
	v_add_f32_e32 v5, v5, v15
	ds_bpermute_b32 v15, v11, v5
	s_waitcnt lgkmcnt(0)
	v_add_f32_e32 v5, v5, v15
	ds_bpermute_b32 v15, v12, v5
	s_and_saveexec_b64 s[0:1], vcc
	s_cbranch_execz .LBB0_413
	s_waitcnt lgkmcnt(0)
	v_add_f32_e32 v5, v5, v15
	global_store_dword v[0:1], v5, off
	s_branch .LBB0_413
